# extended the 4+4 DMA rebalance and setprio removal to the P2 and P7 GEMM loops
# speedup vs baseline: 1.1618x; 1.0041x over previous
; #define PG8_STAGE(bufoff, gbase, voff) do { _Pragma("unroll") for (int _i = 0; _i < 2; ++_i) \
;         __builtin_amdgcn_global_load_lds((const unsigned*)((const char*)(gbase) + (voff)[_i]), (PG8_LAS unsigned*)(lds + (bufoff) + ldsw + _i * 8192), 16, 0, 0); } while (0)
; #define PG8_STAGE_NT(bufoff, gbase, voff) do { _Pragma("unroll") for (int _i = 0; _i < 2; ++_i) \
;         __builtin_amdgcn_global_load_lds((const unsigned*)((const char*)(gbase) + (voff)[_i]), (PG8_LAS unsigned*)(lds + (bufoff) + ldsw + _i * 8192), 16, 0, PG8_B_AUX); } while (0)
; #define PG8_LDA(dst, b, h) do { _Pragma("unroll") for (int m = 0; m < 4; ++m) _Pragma("unroll") for (int k = 0; k < 2; ++k) dst[m][k] = *(const PG8_LAS bf16x8*)(lds + PG8_SA(b, h) + aoff + m * 2048 + k * 1024); } while (0)
; #define PG8_LDB(dst, b, h) do { _Pragma("unroll") for (int n = 0; n < 2; ++n) _Pragma("unroll") for (int k = 0; k < 2; ++k) dst[n][k] = *(const PG8_LAS bf16x8*)(lds + PG8_SB(b, h) + boff + n * 2048 + k * 1024); } while (0)
; #define PG8_WAIT_V(n) asm volatile("s_waitcnt vmcnt(" #n ")" ::: "memory")
; #define PG8_WAIT_L(n) asm volatile("s_waitcnt lgkmcnt(" #n ")" ::: "memory")
; #define PG8_BAR __builtin_amdgcn_s_barrier()
; template <class Epi, class Sched, bool ALIGN_EPI = false, bool SP2 = false>
; __device__ __forceinline__ void gemm_phase(PG8_LAS unsigned char* lds, const Gemm g, const Sched& S, const Epi& E, int wid) {
;     ...
;         for (int t = 0; t < nt; t += 2) {
;             const bool last = (t == nt - 2);
;             const char* a1 = cA + (size_t)(t + 1) * kstep;
;             const char* a2 = last ? nA : cA + (size_t)(t + 2) * kstep; const char* b2 = last ? nB : cB + (size_t)(t + 2) * kstep;
;             const char* a3 = a2 + kstep; const char* b3 = b2 + kstep;
;             if (last && has_next) S.a_ready(nxt);
;             if constexpr (SP2) {
;             PG8_LDB(B0, 0, 0); PG8_LDB(B1, 0, 1); PG8_SCHED; PG8_LDA(At, 0, 0); PG8_STAGE(PG8_SA(1, 1), a1 + hstepA, voffA);
;             PG8_WAIT_V(8); PG8_WAIT_L(0); PG8_BAR; PG8_MMA(0, 0, At, B0); PG8_MMA(0, 1, At, B1); PG8_BAR; PG8_SCHED;
;             PG8_LDA(At, 0, 1); PG8_STAGE_NT(PG8_SB(0, 0), b2, voffB); PG8_STAGE_NT(PG8_SB(0, 1), b2 + hstepB, voffB); PG8_STAGE(PG8_SA(0, 0), a2, voffA);
;             PG8_WAIT_V(8); PG8_WAIT_L(0); PG8_BAR; PG8_MMA(1, 0, At, B0); PG8_MMA(1, 1, At, B1); PG8_BAR; PG8_SCHED;
.LBB0_317:
	ds_read_b128 v[128:131], v205
	ds_read_b128 v[132:135], v205 offset:1024
	ds_read_b128 v[136:139], v205 offset:2048
	ds_read_b128 v[140:143], v205 offset:3072
	ds_read_b128 v[144:147], v206
	ds_read_b128 v[148:151], v206 offset:1024
	ds_read_b128 v[152:155], v206 offset:2048
	ds_read_b128 v[156:159], v206 offset:3072
	s_add_u32 s48, s46, 0x100
	s_addc_u32 s49, s47, 0
	s_add_u32 s98, s46, 0x80
	s_addc_u32 s99, s47, 0
	s_add_u32 s100, s46, 0x2b4080
	s_addc_u32 s101, s47, 0
	s_cmpk_eq_i32 s64, 0xa8
	s_cselect_b32 s53, s7, s49
	s_cselect_b32 s52, s6, s48
	s_cselect_b32 s51, s45, s63
	s_cselect_b32 s50, s44, s62
	s_add_i32 m0, s19, 0xc000
	ds_read_b128 v[160:163], v207
	ds_read_b128 v[164:167], v207 offset:1024
	ds_read_b128 v[184:187], v207 offset:2048
	ds_read_b128 v[188:191], v207 offset:3072
	ds_read_b128 v[192:195], v207 offset:4096
	ds_read_b128 v[196:199], v207 offset:5120
	ds_read_b128 v[210:213], v207 offset:6144
	ds_read_b128 v[214:217], v207 offset:7168
	global_load_lds_dwordx4 v168, s[100:101]
	s_add_i32 m0, s19, 0xe000
	s_nop 0
	global_load_lds_dwordx4 v172, s[100:101]
	s_mov_b32 m0, s29
	s_nop 0
	global_load_lds_dwordx4 v168, s[98:99]
	s_mov_b32 m0, s54
	s_nop 0
	global_load_lds_dwordx4 v172, s[98:99]
	s_waitcnt vmcnt(8)
	s_waitcnt lgkmcnt(0)
	s_barrier
	s_waitcnt lgkmcnt(0)
	v_mfma_f32_16x16x32_bf16 v[124:127], v[128:131], v[160:163], v[124:127]
	v_mfma_f32_16x16x32_bf16 v[120:123], v[136:139], v[160:163], v[120:123]
	v_mfma_f32_16x16x32_bf16 v[116:119], v[128:131], v[184:187], v[116:119]
	v_mfma_f32_16x16x32_bf16 v[112:115], v[136:139], v[184:187], v[112:115]
	v_mfma_f32_16x16x32_bf16 v[92:95], v[128:131], v[192:195], v[92:95]
	v_mfma_f32_16x16x32_bf16 v[88:91], v[136:139], v[192:195], v[88:91]
	v_mfma_f32_16x16x32_bf16 v[76:79], v[128:131], v[210:213], v[76:79]
	v_mfma_f32_16x16x32_bf16 v[72:75], v[136:139], v[210:213], v[72:75]
	v_mfma_f32_16x16x32_bf16 v[124:127], v[132:135], v[164:167], v[124:127]
	v_mfma_f32_16x16x32_bf16 v[120:123], v[140:143], v[164:167], v[120:123]
	v_mfma_f32_16x16x32_bf16 v[116:119], v[132:135], v[188:191], v[116:119]
	v_mfma_f32_16x16x32_bf16 v[112:115], v[140:143], v[188:191], v[112:115]
	v_mfma_f32_16x16x32_bf16 v[92:95], v[132:135], v[196:199], v[92:95]
	v_mfma_f32_16x16x32_bf16 v[88:91], v[140:143], v[196:199], v[88:91]
	v_mfma_f32_16x16x32_bf16 v[76:79], v[132:135], v[214:217], v[76:79]
	v_mfma_f32_16x16x32_bf16 v[72:75], v[140:143], v[214:217], v[72:75]
	v_mfma_f32_16x16x32_bf16 v[108:111], v[144:147], v[160:163], v[108:111]
	v_mfma_f32_16x16x32_bf16 v[104:107], v[152:155], v[160:163], v[104:107]
	v_mfma_f32_16x16x32_bf16 v[100:103], v[144:147], v[184:187], v[100:103]
	v_mfma_f32_16x16x32_bf16 v[96:99], v[152:155], v[184:187], v[96:99]
	v_mfma_f32_16x16x32_bf16 v[84:87], v[144:147], v[192:195], v[84:87]
	v_mfma_f32_16x16x32_bf16 v[80:83], v[152:155], v[192:195], v[80:83]
	v_mfma_f32_16x16x32_bf16 v[68:71], v[144:147], v[210:213], v[68:71]
	v_mfma_f32_16x16x32_bf16 v[64:67], v[152:155], v[210:213], v[64:67]
	v_mfma_f32_16x16x32_bf16 v[108:111], v[148:151], v[164:167], v[108:111]
	v_mfma_f32_16x16x32_bf16 v[104:107], v[156:159], v[164:167], v[104:107]
	v_mfma_f32_16x16x32_bf16 v[100:103], v[148:151], v[188:191], v[100:103]
	v_mfma_f32_16x16x32_bf16 v[96:99], v[156:159], v[188:191], v[96:99]
	v_mfma_f32_16x16x32_bf16 v[84:87], v[148:151], v[196:199], v[84:87]
	v_mfma_f32_16x16x32_bf16 v[80:83], v[156:159], v[196:199], v[80:83]
	v_mfma_f32_16x16x32_bf16 v[68:71], v[148:151], v[214:217], v[68:71]
	v_mfma_f32_16x16x32_bf16 v[64:67], v[156:159], v[214:217], v[64:67]
	s_barrier
	s_add_i32 s46, s57, s17
	s_mov_b32 m0, s46
	ds_read_b128 v[160:163], v207 offset:16384
	ds_read_b128 v[164:167], v207 offset:17408
	ds_read_b128 v[184:187], v207 offset:18432
	ds_read_b128 v[188:191], v207 offset:19456
	ds_read_b128 v[192:195], v207 offset:20480
	ds_read_b128 v[196:199], v207 offset:21504
	ds_read_b128 v[210:213], v207 offset:22528
	ds_read_b128 v[214:217], v207 offset:23552
	global_load_lds_dwordx4 v170, s[50:51]
	s_add_i32 m0, s46, 0x2000
	s_add_u32 s46, s50, 0x2b4000
	s_addc_u32 s47, s51, 0
	s_add_i32 s65, s58, s17
	global_load_lds_dwordx4 v174, s[50:51]
	s_mov_b32 m0, s65
	s_nop 0
	global_load_lds_dwordx4 v170, s[46:47]
	s_add_i32 m0, s65, 0x2000
	s_nop 0
	global_load_lds_dwordx4 v174, s[46:47]
	s_waitcnt vmcnt(4)
	s_waitcnt lgkmcnt(0)
	s_barrier
	s_waitcnt lgkmcnt(0)
	v_mfma_f32_16x16x32_bf16 v[60:63], v[128:131], v[160:163], v[60:63]
	v_mfma_f32_16x16x32_bf16 v[56:59], v[136:139], v[160:163], v[56:59]
	v_mfma_f32_16x16x32_bf16 v[44:47], v[128:131], v[184:187], v[44:47]
	v_mfma_f32_16x16x32_bf16 v[40:43], v[136:139], v[184:187], v[40:43]
	v_mfma_f32_16x16x32_bf16 v[28:31], v[128:131], v[192:195], v[28:31]
	v_mfma_f32_16x16x32_bf16 v[24:27], v[136:139], v[192:195], v[24:27]
	v_mfma_f32_16x16x32_bf16 v[12:15], v[128:131], v[210:213], v[12:15]
	v_mfma_f32_16x16x32_bf16 v[8:11], v[136:139], v[210:213], v[8:11]
	v_mfma_f32_16x16x32_bf16 v[60:63], v[132:135], v[164:167], v[60:63]
	v_mfma_f32_16x16x32_bf16 v[56:59], v[140:143], v[164:167], v[56:59]
	v_mfma_f32_16x16x32_bf16 v[44:47], v[132:135], v[188:191], v[44:47]
	v_mfma_f32_16x16x32_bf16 v[40:43], v[140:143], v[188:191], v[40:43]
	v_mfma_f32_16x16x32_bf16 v[28:31], v[132:135], v[196:199], v[28:31]
	v_mfma_f32_16x16x32_bf16 v[24:27], v[140:143], v[196:199], v[24:27]
	v_mfma_f32_16x16x32_bf16 v[12:15], v[132:135], v[214:217], v[12:15]
	v_mfma_f32_16x16x32_bf16 v[8:11], v[140:143], v[214:217], v[8:11]
	v_mfma_f32_16x16x32_bf16 v[52:55], v[144:147], v[160:163], v[52:55]
	v_mfma_f32_16x16x32_bf16 v[48:51], v[152:155], v[160:163], v[48:51]
	v_mfma_f32_16x16x32_bf16 v[36:39], v[144:147], v[184:187], v[36:39]
	v_mfma_f32_16x16x32_bf16 v[32:35], v[152:155], v[184:187], v[32:35]
	v_mfma_f32_16x16x32_bf16 v[20:23], v[144:147], v[192:195], v[20:23]
	v_mfma_f32_16x16x32_bf16 v[16:19], v[152:155], v[192:195], v[16:19]
	v_mfma_f32_16x16x32_bf16 v[4:7], v[144:147], v[210:213], v[4:7]
	v_mfma_f32_16x16x32_bf16 v[0:3], v[152:155], v[210:213], v[0:3]
	v_mfma_f32_16x16x32_bf16 v[52:55], v[148:151], v[164:167], v[52:55]
	v_mfma_f32_16x16x32_bf16 v[48:51], v[156:159], v[164:167], v[48:51]
	v_mfma_f32_16x16x32_bf16 v[36:39], v[148:151], v[188:191], v[36:39]
	v_mfma_f32_16x16x32_bf16 v[32:35], v[156:159], v[188:191], v[32:35]
	v_mfma_f32_16x16x32_bf16 v[20:23], v[148:151], v[196:199], v[20:23]
	v_mfma_f32_16x16x32_bf16 v[16:19], v[156:159], v[196:199], v[16:19]
	v_mfma_f32_16x16x32_bf16 v[4:7], v[148:151], v[214:217], v[4:7]
	v_mfma_f32_16x16x32_bf16 v[0:3], v[156:159], v[214:217], v[0:3]
	s_barrier
; #define PG8_STAGE(bufoff, gbase, voff) do { _Pragma("unroll") for (int _i = 0; _i < 2; ++_i) \
;         __builtin_amdgcn_global_load_lds((const unsigned*)((const char*)(gbase) + (voff)[_i]), (PG8_LAS unsigned*)(lds + (bufoff) + ldsw + _i * 8192), 16, 0, 0); } while (0)
; template <class Epi, class Sched, bool ALIGN_EPI = false, bool SP2 = false>
; __device__ __forceinline__ void gemm_phase(PG8_LAS unsigned char* lds, const Gemm g, const Sched& S, const Epi& E, int wid) {
;     ...
;             PG8_LDB(B0, 1, 0); PG8_LDB(B1, 1, 1); PG8_SCHED; PG8_LDA(At, 1, 0); PG8_STAGE(PG8_SA(0, 1), a2 + hstepA, voffA);
;             PG8_WAIT_V(8); PG8_WAIT_L(0); PG8_BAR; PG8_MMA(0, 0, At, B0); PG8_MMA(0, 1, At, B1); PG8_BAR; PG8_SCHED;
;             PG8_LDA(At, 1, 1); PG8_STAGE_NT(PG8_SB(1, 0), b3, voffB); PG8_STAGE_NT(PG8_SB(1, 1), b3 + hstepB, voffB); PG8_STAGE(PG8_SA(1, 0), a3, voffA);
;             PG8_WAIT_V(8); PG8_WAIT_L(0); PG8_BAR; PG8_MMA(1, 0, At, B0); PG8_MMA(1, 1, At, B1); PG8_BAR; PG8_SCHED;
;             } else {
;             PG8_LDB(B0, 0, 0); PG8_SCHED; PG8_LDA(At, 0, 0); PG8_STAGE(PG8_SA(1, 1), a1 + hstepA, voffA);
;             PG8_WAIT_L(8); PG8_BAR; PG8_WAIT_L(0); PG8_MMA(0, 0, At, B0); PG8_BAR; PG8_SCHED;
;             PG8_LDB(B1, 0, 1); PG8_STAGE_NT(PG8_SB(0, 0), b2, voffB);
;             PG8_BAR; PG8_WAIT_L(0); PG8_MMA(0, 1, At, B1); PG8_BAR;
;             PG8_LDA(At, 0, 1); PG8_STAGE(PG8_SA(0, 0), a2, voffA);
;             PG8_BAR; PG8_WAIT_L(0); PG8_MMA(1, 0, At, B0); PG8_BAR; PG8_SCHED;
;             PG8_STAGE_NT(PG8_SB(0, 1), b2 + hstepB, voffB);
;             PG8_WAIT_V(6); PG8_BAR; PG8_MMA(1, 1, At, B1); PG8_BAR;
;             PG8_LDB(B0, 1, 0); PG8_SCHED; PG8_LDA(At, 1, 0); PG8_STAGE(PG8_SA(0, 1), a2 + hstepA, voffA);
;             PG8_WAIT_L(8); PG8_BAR; PG8_WAIT_L(0); PG8_MMA(0, 0, At, B0); PG8_BAR; PG8_SCHED;
;             PG8_LDB(B1, 1, 1); PG8_STAGE_NT(PG8_SB(1, 0), b3, voffB);
;             PG8_BAR; PG8_WAIT_L(0); PG8_MMA(0, 1, At, B1); PG8_BAR;
;             PG8_LDA(At, 1, 1); PG8_STAGE(PG8_SA(1, 0), a3, voffA);
;             PG8_BAR; PG8_WAIT_L(0); PG8_MMA(1, 0, At, B0); PG8_BAR; PG8_SCHED;
;             PG8_STAGE_NT(PG8_SB(1, 1), b3 + hstepB, voffB);
;             PG8_WAIT_V(6); PG8_BAR; PG8_MMA(1, 1, At, B1); PG8_BAR;
;             }
;         }
;         if constexpr (ALIGN_EPI) { if (wr == 0) PG8_BAR; }
	s_add_i32 s65, 0, 0x18000
	v_add_u32_e32 v140, s65, v203
	s_add_i32 s66, 0, 0x1c000
	ds_read_b128 v[128:131], v140
	ds_read_b128 v[132:135], v140 offset:1024
	ds_read_b128 v[136:139], v140 offset:2048
	ds_read_b128 v[140:143], v140 offset:3072
	v_add_u32_e32 v156, s66, v203
	ds_read_b128 v[144:147], v156
	ds_read_b128 v[148:151], v156 offset:1024
	ds_read_b128 v[152:155], v156 offset:2048
	ds_read_b128 v[156:159], v156 offset:3072
	s_add_u32 s46, s52, 0x2b4000
	s_addc_u32 s47, s53, 0
	s_mov_b32 m0, s23
	ds_read_b128 v[160:163], v207 offset:32768
	ds_read_b128 v[164:167], v207 offset:33792
	ds_read_b128 v[184:187], v207 offset:34816
	ds_read_b128 v[188:191], v207 offset:35840
	ds_read_b128 v[192:195], v207 offset:36864
	ds_read_b128 v[196:199], v207 offset:37888
	ds_read_b128 v[210:213], v207 offset:38912
	ds_read_b128 v[214:217], v207 offset:39936
	global_load_lds_dwordx4 v168, s[46:47]
	s_mov_b32 m0, s24
	s_nop 0
	global_load_lds_dwordx4 v172, s[46:47]
	s_mov_b32 m0, s19
	s_nop 0
	global_load_lds_dwordx4 v168, s[52:53]
	s_mov_b32 m0, s22
	s_nop 0
	global_load_lds_dwordx4 v172, s[52:53]
	s_waitcnt vmcnt(8)
	s_waitcnt lgkmcnt(0)
	s_barrier
	s_waitcnt lgkmcnt(0)
	v_mfma_f32_16x16x32_bf16 v[124:127], v[128:131], v[160:163], v[124:127]
	v_mfma_f32_16x16x32_bf16 v[120:123], v[136:139], v[160:163], v[120:123]
	v_mfma_f32_16x16x32_bf16 v[116:119], v[128:131], v[184:187], v[116:119]
	v_mfma_f32_16x16x32_bf16 v[112:115], v[136:139], v[184:187], v[112:115]
	v_mfma_f32_16x16x32_bf16 v[92:95], v[128:131], v[192:195], v[92:95]
	v_mfma_f32_16x16x32_bf16 v[88:91], v[136:139], v[192:195], v[88:91]
	v_mfma_f32_16x16x32_bf16 v[76:79], v[128:131], v[210:213], v[76:79]
	v_mfma_f32_16x16x32_bf16 v[72:75], v[136:139], v[210:213], v[72:75]
	v_mfma_f32_16x16x32_bf16 v[124:127], v[132:135], v[164:167], v[124:127]
	v_mfma_f32_16x16x32_bf16 v[120:123], v[140:143], v[164:167], v[120:123]
	v_mfma_f32_16x16x32_bf16 v[116:119], v[132:135], v[188:191], v[116:119]
	v_mfma_f32_16x16x32_bf16 v[112:115], v[140:143], v[188:191], v[112:115]
	v_mfma_f32_16x16x32_bf16 v[92:95], v[132:135], v[196:199], v[92:95]
	v_mfma_f32_16x16x32_bf16 v[88:91], v[140:143], v[196:199], v[88:91]
	v_mfma_f32_16x16x32_bf16 v[76:79], v[132:135], v[214:217], v[76:79]
	v_mfma_f32_16x16x32_bf16 v[72:75], v[140:143], v[214:217], v[72:75]
	v_mfma_f32_16x16x32_bf16 v[108:111], v[144:147], v[160:163], v[108:111]
	v_mfma_f32_16x16x32_bf16 v[104:107], v[152:155], v[160:163], v[104:107]
	v_mfma_f32_16x16x32_bf16 v[100:103], v[144:147], v[184:187], v[100:103]
	v_mfma_f32_16x16x32_bf16 v[96:99], v[152:155], v[184:187], v[96:99]
	v_mfma_f32_16x16x32_bf16 v[84:87], v[144:147], v[192:195], v[84:87]
	v_mfma_f32_16x16x32_bf16 v[80:83], v[152:155], v[192:195], v[80:83]
	v_mfma_f32_16x16x32_bf16 v[68:71], v[144:147], v[210:213], v[68:71]
	v_mfma_f32_16x16x32_bf16 v[64:67], v[152:155], v[210:213], v[64:67]
	v_mfma_f32_16x16x32_bf16 v[108:111], v[148:151], v[164:167], v[108:111]
	v_mfma_f32_16x16x32_bf16 v[104:107], v[156:159], v[164:167], v[104:107]
	v_mfma_f32_16x16x32_bf16 v[100:103], v[148:151], v[188:191], v[100:103]
	v_mfma_f32_16x16x32_bf16 v[96:99], v[156:159], v[188:191], v[96:99]
	v_mfma_f32_16x16x32_bf16 v[84:87], v[148:151], v[196:199], v[84:87]
	v_mfma_f32_16x16x32_bf16 v[80:83], v[156:159], v[196:199], v[80:83]
	v_mfma_f32_16x16x32_bf16 v[68:71], v[148:151], v[214:217], v[68:71]
	v_mfma_f32_16x16x32_bf16 v[64:67], v[156:159], v[214:217], v[64:67]
	s_barrier
	s_add_i32 s46, s65, s17
	s_mov_b32 m0, s46
	s_add_u32 s98, s50, 0x80
	s_addc_u32 s99, s51, 0
	ds_read_b128 v[160:163], v207 offset:49152
	ds_read_b128 v[164:167], v207 offset:50176
	ds_read_b128 v[184:187], v207 offset:51200
	ds_read_b128 v[188:191], v207 offset:52224
	ds_read_b128 v[192:195], v207 offset:53248
	ds_read_b128 v[196:199], v207 offset:54272
	ds_read_b128 v[210:213], v207 offset:55296
	ds_read_b128 v[214:217], v207 offset:56320
	global_load_lds_dwordx4 v170, s[98:99]
	s_add_i32 m0, s46, 0x2000
	s_add_u32 s46, s50, 0x2b4080
	s_addc_u32 s47, s51, 0
	s_add_i32 s50, s66, s17
	global_load_lds_dwordx4 v174, s[98:99]
	s_mov_b32 m0, s50
	s_nop 0
	global_load_lds_dwordx4 v170, s[46:47]
	s_add_i32 m0, s50, 0x2000
	s_nop 0
	global_load_lds_dwordx4 v174, s[46:47]
	s_waitcnt vmcnt(4)
	s_waitcnt lgkmcnt(0)
	s_barrier
	s_waitcnt lgkmcnt(0)
	v_mfma_f32_16x16x32_bf16 v[60:63], v[128:131], v[160:163], v[60:63]
	v_mfma_f32_16x16x32_bf16 v[56:59], v[136:139], v[160:163], v[56:59]
	v_mfma_f32_16x16x32_bf16 v[44:47], v[128:131], v[184:187], v[44:47]
	v_mfma_f32_16x16x32_bf16 v[40:43], v[136:139], v[184:187], v[40:43]
	v_mfma_f32_16x16x32_bf16 v[28:31], v[128:131], v[192:195], v[28:31]
	v_mfma_f32_16x16x32_bf16 v[24:27], v[136:139], v[192:195], v[24:27]
	v_mfma_f32_16x16x32_bf16 v[12:15], v[128:131], v[210:213], v[12:15]
	v_mfma_f32_16x16x32_bf16 v[8:11], v[136:139], v[210:213], v[8:11]
	v_mfma_f32_16x16x32_bf16 v[60:63], v[132:135], v[164:167], v[60:63]
	v_mfma_f32_16x16x32_bf16 v[56:59], v[140:143], v[164:167], v[56:59]
	v_mfma_f32_16x16x32_bf16 v[44:47], v[132:135], v[188:191], v[44:47]
	v_mfma_f32_16x16x32_bf16 v[40:43], v[140:143], v[188:191], v[40:43]
	v_mfma_f32_16x16x32_bf16 v[28:31], v[132:135], v[196:199], v[28:31]
	v_mfma_f32_16x16x32_bf16 v[24:27], v[140:143], v[196:199], v[24:27]
	v_mfma_f32_16x16x32_bf16 v[12:15], v[132:135], v[214:217], v[12:15]
	v_mfma_f32_16x16x32_bf16 v[8:11], v[140:143], v[214:217], v[8:11]
	v_mfma_f32_16x16x32_bf16 v[52:55], v[144:147], v[160:163], v[52:55]
	v_mfma_f32_16x16x32_bf16 v[48:51], v[152:155], v[160:163], v[48:51]
	v_mfma_f32_16x16x32_bf16 v[36:39], v[144:147], v[184:187], v[36:39]
	v_mfma_f32_16x16x32_bf16 v[32:35], v[152:155], v[184:187], v[32:35]
	v_mfma_f32_16x16x32_bf16 v[20:23], v[144:147], v[192:195], v[20:23]
	v_mfma_f32_16x16x32_bf16 v[16:19], v[152:155], v[192:195], v[16:19]
	v_mfma_f32_16x16x32_bf16 v[4:7], v[144:147], v[210:213], v[4:7]
	v_mfma_f32_16x16x32_bf16 v[0:3], v[152:155], v[210:213], v[0:3]
	v_mfma_f32_16x16x32_bf16 v[52:55], v[148:151], v[164:167], v[52:55]
	v_mfma_f32_16x16x32_bf16 v[48:51], v[156:159], v[164:167], v[48:51]
	v_mfma_f32_16x16x32_bf16 v[36:39], v[148:151], v[188:191], v[36:39]
	v_mfma_f32_16x16x32_bf16 v[32:35], v[156:159], v[188:191], v[32:35]
	v_mfma_f32_16x16x32_bf16 v[20:23], v[148:151], v[196:199], v[20:23]
	v_mfma_f32_16x16x32_bf16 v[16:19], v[156:159], v[196:199], v[16:19]
	v_mfma_f32_16x16x32_bf16 v[4:7], v[148:151], v[214:217], v[4:7]
	v_mfma_f32_16x16x32_bf16 v[0:3], v[156:159], v[214:217], v[0:3]
	s_barrier
	s_add_i32 s64, s64, 2
	s_add_u32 s62, s62, 0x100
	s_addc_u32 s63, s63, 0
	s_cmpk_gt_u32 s64, 0xa9
	s_mov_b64 s[46:47], s[48:49]
	s_cbranch_scc0 .LBB0_317
	s_and_b64 vcc, exec, s[42:43]
	s_cbranch_vccz .LBB0_320
	s_barrier

; #define PG8_STAGE(bufoff, gbase, voff) do { _Pragma("unroll") for (int _i = 0; _i < 2; ++_i) \
;         __builtin_amdgcn_global_load_lds((const unsigned*)((const char*)(gbase) + (voff)[_i]), (PG8_LAS unsigned*)(lds + (bufoff) + ldsw + _i * 8192), 16, 0, 0); } while (0)
; #define PG8_STAGE_NT(bufoff, gbase, voff) do { _Pragma("unroll") for (int _i = 0; _i < 2; ++_i) \
;         __builtin_amdgcn_global_load_lds((const unsigned*)((const char*)(gbase) + (voff)[_i]), (PG8_LAS unsigned*)(lds + (bufoff) + ldsw + _i * 8192), 16, 0, PG8_B_AUX); } while (0)
; #define PG8_LDA(dst, b, h) do { _Pragma("unroll") for (int m = 0; m < 4; ++m) _Pragma("unroll") for (int k = 0; k < 2; ++k) dst[m][k] = *(const PG8_LAS bf16x8*)(lds + PG8_SA(b, h) + aoff + m * 2048 + k * 1024); } while (0)
; #define PG8_LDB(dst, b, h) do { _Pragma("unroll") for (int n = 0; n < 2; ++n) _Pragma("unroll") for (int k = 0; k < 2; ++k) dst[n][k] = *(const PG8_LAS bf16x8*)(lds + PG8_SB(b, h) + boff + n * 2048 + k * 1024); } while (0)
; #define PG8_WAIT_V(n) asm volatile("s_waitcnt vmcnt(" #n ")" ::: "memory")
; #define PG8_WAIT_L(n) asm volatile("s_waitcnt lgkmcnt(" #n ")" ::: "memory")
; #define PG8_BAR __builtin_amdgcn_s_barrier()
; template <class Epi, class Sched, bool ALIGN_EPI = false, bool SP2 = false>
; __device__ __forceinline__ void gemm_phase(PG8_LAS unsigned char* lds, const Gemm g, const Sched& S, const Epi& E, int wid) {
;     ...
;         for (int t = 0; t < nt; t += 2) {
;             const bool last = (t == nt - 2);
;             const char* a1 = cA + (size_t)(t + 1) * kstep;
;             const char* a2 = last ? nA : cA + (size_t)(t + 2) * kstep; const char* b2 = last ? nB : cB + (size_t)(t + 2) * kstep;
;             const char* a3 = a2 + kstep; const char* b3 = b2 + kstep;
;             if (last && has_next) S.a_ready(nxt);
;             if constexpr (SP2) {
;             PG8_LDB(B0, 0, 0); PG8_LDB(B1, 0, 1); PG8_SCHED; PG8_LDA(At, 0, 0); PG8_STAGE(PG8_SA(1, 1), a1 + hstepA, voffA);
;             PG8_WAIT_V(8); PG8_WAIT_L(0); PG8_BAR; PG8_MMA(0, 0, At, B0); PG8_MMA(0, 1, At, B1); PG8_BAR; PG8_SCHED;
;             PG8_LDA(At, 0, 1); PG8_STAGE_NT(PG8_SB(0, 0), b2, voffB); PG8_STAGE_NT(PG8_SB(0, 1), b2 + hstepB, voffB); PG8_STAGE(PG8_SA(0, 0), a2, voffA);
;             PG8_WAIT_V(8); PG8_WAIT_L(0); PG8_BAR; PG8_MMA(1, 0, At, B0); PG8_MMA(1, 1, At, B1); PG8_BAR; PG8_SCHED;
.LBB0_1037:
	ds_read_b128 v[104:107], v221
	ds_read_b128 v[116:119], v221 offset:1024
	ds_read_b128 v[128:131], v221 offset:2048
	ds_read_b128 v[140:143], v221 offset:3072
	ds_read_b128 v[144:147], v222
	ds_read_b128 v[148:151], v222 offset:1024
	ds_read_b128 v[152:155], v222 offset:2048
	ds_read_b128 v[156:159], v222 offset:3072
	s_add_u32 s52, s50, 0x100
	s_addc_u32 s53, s51, 0
	s_add_u32 s98, s50, 0x80
	s_addc_u32 s99, s51, 0
	s_add_u32 s100, s50, 0x104080
	s_addc_u32 s101, s51, 0
	s_cmp_eq_u32 s67, 60
	s_cselect_b32 s57, s7, s53
	s_cselect_b32 s56, s6, s52
	s_cselect_b32 s55, s49, s66
	s_cselect_b32 s54, s48, s65
	s_add_i32 m0, s17, 0xc000
	ds_read_b128 v[160:163], v223
	ds_read_b128 v[164:167], v223 offset:1024
	ds_read_b128 v[168:171], v223 offset:2048
	ds_read_b128 v[172:175], v223 offset:3072
	ds_read_b128 v[176:179], v223 offset:4096
	ds_read_b128 v[180:183], v223 offset:5120
	ds_read_b128 v[200:203], v223 offset:6144
	ds_read_b128 v[204:207], v223 offset:7168
	global_load_lds_dwordx4 v184, s[100:101]
	s_add_i32 m0, s17, 0xe000
	s_nop 0
	global_load_lds_dwordx4 v188, s[100:101]
	s_mov_b32 m0, s25
	s_nop 0
	global_load_lds_dwordx4 v184, s[98:99]
	s_mov_b32 m0, s29
	s_nop 0
	global_load_lds_dwordx4 v188, s[98:99]
	s_waitcnt vmcnt(8)
	s_waitcnt lgkmcnt(0)
	s_barrier
	s_waitcnt lgkmcnt(0)
	v_mfma_f32_16x16x32_bf16 v[136:139], v[104:107], v[160:163], v[136:139]
	v_mfma_f32_16x16x32_bf16 v[132:135], v[128:131], v[160:163], v[132:135]
	v_mfma_f32_16x16x32_bf16 v[112:115], v[104:107], v[168:171], v[112:115]
	v_mfma_f32_16x16x32_bf16 v[108:111], v[128:131], v[168:171], v[108:111]
	v_mfma_f32_16x16x32_bf16 v[92:95], v[104:107], v[176:179], v[92:95]
	v_mfma_f32_16x16x32_bf16 v[88:91], v[128:131], v[176:179], v[88:91]
	v_mfma_f32_16x16x32_bf16 v[76:79], v[104:107], v[200:203], v[76:79]
	v_mfma_f32_16x16x32_bf16 v[72:75], v[128:131], v[200:203], v[72:75]
	v_mfma_f32_16x16x32_bf16 v[136:139], v[116:119], v[164:167], v[136:139]
	v_mfma_f32_16x16x32_bf16 v[132:135], v[140:143], v[164:167], v[132:135]
	v_mfma_f32_16x16x32_bf16 v[112:115], v[116:119], v[172:175], v[112:115]
	v_mfma_f32_16x16x32_bf16 v[108:111], v[140:143], v[172:175], v[108:111]
	v_mfma_f32_16x16x32_bf16 v[92:95], v[116:119], v[180:183], v[92:95]
	v_mfma_f32_16x16x32_bf16 v[88:91], v[140:143], v[180:183], v[88:91]
	v_mfma_f32_16x16x32_bf16 v[76:79], v[116:119], v[204:207], v[76:79]
	v_mfma_f32_16x16x32_bf16 v[72:75], v[140:143], v[204:207], v[72:75]
	v_mfma_f32_16x16x32_bf16 v[124:127], v[144:147], v[160:163], v[124:127]
	v_mfma_f32_16x16x32_bf16 v[120:123], v[152:155], v[160:163], v[120:123]
	v_mfma_f32_16x16x32_bf16 v[100:103], v[144:147], v[168:171], v[100:103]
	v_mfma_f32_16x16x32_bf16 v[96:99], v[152:155], v[168:171], v[96:99]
	v_mfma_f32_16x16x32_bf16 v[84:87], v[144:147], v[176:179], v[84:87]
	v_mfma_f32_16x16x32_bf16 v[80:83], v[152:155], v[176:179], v[80:83]
	v_mfma_f32_16x16x32_bf16 v[68:71], v[144:147], v[200:203], v[68:71]
	v_mfma_f32_16x16x32_bf16 v[64:67], v[152:155], v[200:203], v[64:67]
	v_mfma_f32_16x16x32_bf16 v[124:127], v[148:151], v[164:167], v[124:127]
	v_mfma_f32_16x16x32_bf16 v[120:123], v[156:159], v[164:167], v[120:123]
	v_mfma_f32_16x16x32_bf16 v[100:103], v[148:151], v[172:175], v[100:103]
	v_mfma_f32_16x16x32_bf16 v[96:99], v[156:159], v[172:175], v[96:99]
	v_mfma_f32_16x16x32_bf16 v[84:87], v[148:151], v[180:183], v[84:87]
	v_mfma_f32_16x16x32_bf16 v[80:83], v[156:159], v[180:183], v[80:83]
	v_mfma_f32_16x16x32_bf16 v[68:71], v[148:151], v[204:207], v[68:71]
	v_mfma_f32_16x16x32_bf16 v[64:67], v[156:159], v[204:207], v[64:67]
	s_barrier
	s_add_i32 s50, s60, s9
	s_mov_b32 m0, s50
	ds_read_b128 v[160:163], v223 offset:16384
	ds_read_b128 v[164:167], v223 offset:17408
	ds_read_b128 v[168:171], v223 offset:18432
	ds_read_b128 v[172:175], v223 offset:19456
	ds_read_b128 v[176:179], v223 offset:20480
	ds_read_b128 v[180:183], v223 offset:21504
	ds_read_b128 v[200:203], v223 offset:22528
	ds_read_b128 v[204:207], v223 offset:23552
	global_load_lds_dwordx4 v186, s[54:55]
	s_add_i32 m0, s50, 0x2000
	s_add_u32 s50, s54, 0x104000
	s_addc_u32 s51, s55, 0
	s_add_i32 s68, s61, s9
	global_load_lds_dwordx4 v190, s[54:55]
	s_mov_b32 m0, s68
	s_nop 0
	global_load_lds_dwordx4 v186, s[50:51]
	s_add_i32 m0, s68, 0x2000
	s_nop 0
	global_load_lds_dwordx4 v190, s[50:51]
	s_waitcnt vmcnt(4)
	s_waitcnt lgkmcnt(0)
	s_barrier
	s_waitcnt lgkmcnt(0)
	v_mfma_f32_16x16x32_bf16 v[60:63], v[104:107], v[160:163], v[60:63]
	v_mfma_f32_16x16x32_bf16 v[56:59], v[128:131], v[160:163], v[56:59]
	v_mfma_f32_16x16x32_bf16 v[44:47], v[104:107], v[168:171], v[44:47]
	v_mfma_f32_16x16x32_bf16 v[40:43], v[128:131], v[168:171], v[40:43]
	v_mfma_f32_16x16x32_bf16 v[28:31], v[104:107], v[176:179], v[28:31]
	v_mfma_f32_16x16x32_bf16 v[24:27], v[128:131], v[176:179], v[24:27]
	v_mfma_f32_16x16x32_bf16 v[12:15], v[104:107], v[200:203], v[12:15]
	v_mfma_f32_16x16x32_bf16 v[8:11], v[128:131], v[200:203], v[8:11]
	v_mfma_f32_16x16x32_bf16 v[60:63], v[116:119], v[164:167], v[60:63]
	v_mfma_f32_16x16x32_bf16 v[56:59], v[140:143], v[164:167], v[56:59]
	v_mfma_f32_16x16x32_bf16 v[44:47], v[116:119], v[172:175], v[44:47]
	v_mfma_f32_16x16x32_bf16 v[40:43], v[140:143], v[172:175], v[40:43]
	v_mfma_f32_16x16x32_bf16 v[28:31], v[116:119], v[180:183], v[28:31]
	v_mfma_f32_16x16x32_bf16 v[24:27], v[140:143], v[180:183], v[24:27]
	v_mfma_f32_16x16x32_bf16 v[12:15], v[116:119], v[204:207], v[12:15]
	v_mfma_f32_16x16x32_bf16 v[8:11], v[140:143], v[204:207], v[8:11]
	v_mfma_f32_16x16x32_bf16 v[52:55], v[144:147], v[160:163], v[52:55]
	v_mfma_f32_16x16x32_bf16 v[48:51], v[152:155], v[160:163], v[48:51]
	v_mfma_f32_16x16x32_bf16 v[36:39], v[144:147], v[168:171], v[36:39]
	v_mfma_f32_16x16x32_bf16 v[32:35], v[152:155], v[168:171], v[32:35]
	v_mfma_f32_16x16x32_bf16 v[20:23], v[144:147], v[176:179], v[20:23]
	v_mfma_f32_16x16x32_bf16 v[16:19], v[152:155], v[176:179], v[16:19]
	v_mfma_f32_16x16x32_bf16 v[4:7], v[144:147], v[200:203], v[4:7]
	v_mfma_f32_16x16x32_bf16 v[0:3], v[152:155], v[200:203], v[0:3]
	v_mfma_f32_16x16x32_bf16 v[52:55], v[148:151], v[164:167], v[52:55]
	v_mfma_f32_16x16x32_bf16 v[48:51], v[156:159], v[164:167], v[48:51]
	v_mfma_f32_16x16x32_bf16 v[36:39], v[148:151], v[172:175], v[36:39]
	v_mfma_f32_16x16x32_bf16 v[32:35], v[156:159], v[172:175], v[32:35]
	v_mfma_f32_16x16x32_bf16 v[20:23], v[148:151], v[180:183], v[20:23]
	v_mfma_f32_16x16x32_bf16 v[16:19], v[156:159], v[180:183], v[16:19]
	v_mfma_f32_16x16x32_bf16 v[4:7], v[148:151], v[204:207], v[4:7]
	v_mfma_f32_16x16x32_bf16 v[0:3], v[156:159], v[204:207], v[0:3]
	s_barrier
; #define PG8_STAGE(bufoff, gbase, voff) do { _Pragma("unroll") for (int _i = 0; _i < 2; ++_i) \
;         __builtin_amdgcn_global_load_lds((const unsigned*)((const char*)(gbase) + (voff)[_i]), (PG8_LAS unsigned*)(lds + (bufoff) + ldsw + _i * 8192), 16, 0, 0); } while (0)
; template <class Epi, class Sched, bool ALIGN_EPI = false, bool SP2 = false>
; __device__ __forceinline__ void gemm_phase(PG8_LAS unsigned char* lds, const Gemm g, const Sched& S, const Epi& E, int wid) {
;     ...
;             PG8_LDB(B0, 1, 0); PG8_LDB(B1, 1, 1); PG8_SCHED; PG8_LDA(At, 1, 0); PG8_STAGE(PG8_SA(0, 1), a2 + hstepA, voffA);
;             PG8_WAIT_V(8); PG8_WAIT_L(0); PG8_BAR; PG8_MMA(0, 0, At, B0); PG8_MMA(0, 1, At, B1); PG8_BAR; PG8_SCHED;
;             PG8_LDA(At, 1, 1); PG8_STAGE_NT(PG8_SB(1, 0), b3, voffB); PG8_STAGE_NT(PG8_SB(1, 1), b3 + hstepB, voffB); PG8_STAGE(PG8_SA(1, 0), a3, voffA);
;             PG8_WAIT_V(8); PG8_WAIT_L(0); PG8_BAR; PG8_MMA(1, 0, At, B0); PG8_MMA(1, 1, At, B1); PG8_BAR; PG8_SCHED;
;             } else {
;             PG8_LDB(B0, 0, 0); PG8_SCHED; PG8_LDA(At, 0, 0); PG8_STAGE(PG8_SA(1, 1), a1 + hstepA, voffA);
;             PG8_WAIT_L(8); PG8_BAR; PG8_WAIT_L(0); PG8_MMA(0, 0, At, B0); PG8_BAR; PG8_SCHED;
;             PG8_LDB(B1, 0, 1); PG8_STAGE_NT(PG8_SB(0, 0), b2, voffB);
;             PG8_BAR; PG8_WAIT_L(0); PG8_MMA(0, 1, At, B1); PG8_BAR;
;             PG8_LDA(At, 0, 1); PG8_STAGE(PG8_SA(0, 0), a2, voffA);
;             PG8_BAR; PG8_WAIT_L(0); PG8_MMA(1, 0, At, B0); PG8_BAR; PG8_SCHED;
;             PG8_STAGE_NT(PG8_SB(0, 1), b2 + hstepB, voffB);
;             PG8_WAIT_V(6); PG8_BAR; PG8_MMA(1, 1, At, B1); PG8_BAR;
;             PG8_LDB(B0, 1, 0); PG8_SCHED; PG8_LDA(At, 1, 0); PG8_STAGE(PG8_SA(0, 1), a2 + hstepA, voffA);
;             PG8_WAIT_L(8); PG8_BAR; PG8_WAIT_L(0); PG8_MMA(0, 0, At, B0); PG8_BAR; PG8_SCHED;
;             PG8_LDB(B1, 1, 1); PG8_STAGE_NT(PG8_SB(1, 0), b3, voffB);
;             PG8_BAR; PG8_WAIT_L(0); PG8_MMA(0, 1, At, B1); PG8_BAR;
;             PG8_LDA(At, 1, 1); PG8_STAGE(PG8_SA(1, 0), a3, voffA);
;             PG8_BAR; PG8_WAIT_L(0); PG8_MMA(1, 0, At, B0); PG8_BAR; PG8_SCHED;
;             PG8_STAGE_NT(PG8_SB(1, 1), b3 + hstepB, voffB);
;             PG8_WAIT_V(6); PG8_BAR; PG8_MMA(1, 1, At, B1); PG8_BAR;
;             }
;         }
;         if constexpr (ALIGN_EPI) { if (wr == 0) PG8_BAR; }
	s_add_i32 s68, 0, 0x18000
	v_add_u32_e32 v140, s68, v219
	s_add_i32 s69, 0, 0x1c000
	ds_read_b128 v[104:107], v140
	ds_read_b128 v[116:119], v140 offset:1024
	ds_read_b128 v[128:131], v140 offset:2048
	ds_read_b128 v[140:143], v140 offset:3072
	v_add_u32_e32 v156, s69, v219
	ds_read_b128 v[144:147], v156
	ds_read_b128 v[148:151], v156 offset:1024
	ds_read_b128 v[152:155], v156 offset:2048
	ds_read_b128 v[156:159], v156 offset:3072
	s_add_u32 s50, s56, 0x104000
	s_addc_u32 s51, s57, 0
	s_mov_b32 m0, s22
	ds_read_b128 v[160:163], v223 offset:32768
	ds_read_b128 v[164:167], v223 offset:33792
	ds_read_b128 v[168:171], v223 offset:34816
	ds_read_b128 v[172:175], v223 offset:35840
	ds_read_b128 v[176:179], v223 offset:36864
	ds_read_b128 v[180:183], v223 offset:37888
	ds_read_b128 v[200:203], v223 offset:38912
	ds_read_b128 v[204:207], v223 offset:39936
	global_load_lds_dwordx4 v184, s[50:51]
	s_mov_b32 m0, s23
	s_nop 0
	global_load_lds_dwordx4 v188, s[50:51]
	s_mov_b32 m0, s17
	s_nop 0
	global_load_lds_dwordx4 v184, s[56:57]
	s_mov_b32 m0, s19
	s_nop 0
	global_load_lds_dwordx4 v188, s[56:57]
	s_waitcnt vmcnt(8)
	s_waitcnt lgkmcnt(0)
	s_barrier
	s_waitcnt lgkmcnt(0)
	v_mfma_f32_16x16x32_bf16 v[136:139], v[104:107], v[160:163], v[136:139]
	v_mfma_f32_16x16x32_bf16 v[132:135], v[128:131], v[160:163], v[132:135]
	v_mfma_f32_16x16x32_bf16 v[112:115], v[104:107], v[168:171], v[112:115]
	v_mfma_f32_16x16x32_bf16 v[108:111], v[128:131], v[168:171], v[108:111]
	v_mfma_f32_16x16x32_bf16 v[92:95], v[104:107], v[176:179], v[92:95]
	v_mfma_f32_16x16x32_bf16 v[88:91], v[128:131], v[176:179], v[88:91]
	v_mfma_f32_16x16x32_bf16 v[76:79], v[104:107], v[200:203], v[76:79]
	v_mfma_f32_16x16x32_bf16 v[72:75], v[128:131], v[200:203], v[72:75]
	v_mfma_f32_16x16x32_bf16 v[136:139], v[116:119], v[164:167], v[136:139]
	v_mfma_f32_16x16x32_bf16 v[132:135], v[140:143], v[164:167], v[132:135]
	v_mfma_f32_16x16x32_bf16 v[112:115], v[116:119], v[172:175], v[112:115]
	v_mfma_f32_16x16x32_bf16 v[108:111], v[140:143], v[172:175], v[108:111]
	v_mfma_f32_16x16x32_bf16 v[92:95], v[116:119], v[180:183], v[92:95]
	v_mfma_f32_16x16x32_bf16 v[88:91], v[140:143], v[180:183], v[88:91]
	v_mfma_f32_16x16x32_bf16 v[76:79], v[116:119], v[204:207], v[76:79]
	v_mfma_f32_16x16x32_bf16 v[72:75], v[140:143], v[204:207], v[72:75]
	v_mfma_f32_16x16x32_bf16 v[124:127], v[144:147], v[160:163], v[124:127]
	v_mfma_f32_16x16x32_bf16 v[120:123], v[152:155], v[160:163], v[120:123]
	v_mfma_f32_16x16x32_bf16 v[100:103], v[144:147], v[168:171], v[100:103]
	v_mfma_f32_16x16x32_bf16 v[96:99], v[152:155], v[168:171], v[96:99]
	v_mfma_f32_16x16x32_bf16 v[84:87], v[144:147], v[176:179], v[84:87]
	v_mfma_f32_16x16x32_bf16 v[80:83], v[152:155], v[176:179], v[80:83]
	v_mfma_f32_16x16x32_bf16 v[68:71], v[144:147], v[200:203], v[68:71]
	v_mfma_f32_16x16x32_bf16 v[64:67], v[152:155], v[200:203], v[64:67]
	v_mfma_f32_16x16x32_bf16 v[124:127], v[148:151], v[164:167], v[124:127]
	v_mfma_f32_16x16x32_bf16 v[120:123], v[156:159], v[164:167], v[120:123]
	v_mfma_f32_16x16x32_bf16 v[100:103], v[148:151], v[172:175], v[100:103]
	v_mfma_f32_16x16x32_bf16 v[96:99], v[156:159], v[172:175], v[96:99]
	v_mfma_f32_16x16x32_bf16 v[84:87], v[148:151], v[180:183], v[84:87]
	v_mfma_f32_16x16x32_bf16 v[80:83], v[156:159], v[180:183], v[80:83]
	v_mfma_f32_16x16x32_bf16 v[68:71], v[148:151], v[204:207], v[68:71]
	v_mfma_f32_16x16x32_bf16 v[64:67], v[156:159], v[204:207], v[64:67]
	s_barrier
	s_add_i32 s50, s68, s9
	s_mov_b32 m0, s50
	s_add_u32 s98, s54, 0x80
	s_addc_u32 s99, s55, 0
	ds_read_b128 v[160:163], v223 offset:49152
	ds_read_b128 v[164:167], v223 offset:50176
	ds_read_b128 v[168:171], v223 offset:51200
	ds_read_b128 v[172:175], v223 offset:52224
	ds_read_b128 v[176:179], v223 offset:53248
	ds_read_b128 v[180:183], v223 offset:54272
	ds_read_b128 v[200:203], v223 offset:55296
	ds_read_b128 v[204:207], v223 offset:56320
	global_load_lds_dwordx4 v186, s[98:99]
	s_add_i32 m0, s50, 0x2000
	s_add_u32 s50, s54, 0x104080
	s_addc_u32 s51, s55, 0
	s_add_i32 s54, s69, s9
	global_load_lds_dwordx4 v190, s[98:99]
	s_mov_b32 m0, s54
	s_nop 0
	global_load_lds_dwordx4 v186, s[50:51]
	s_add_i32 m0, s54, 0x2000
	s_nop 0
	global_load_lds_dwordx4 v190, s[50:51]
	s_waitcnt vmcnt(4)
	s_waitcnt lgkmcnt(0)
	s_barrier
	s_waitcnt lgkmcnt(0)
	v_mfma_f32_16x16x32_bf16 v[60:63], v[104:107], v[160:163], v[60:63]
	v_mfma_f32_16x16x32_bf16 v[56:59], v[128:131], v[160:163], v[56:59]
	v_mfma_f32_16x16x32_bf16 v[44:47], v[104:107], v[168:171], v[44:47]
	v_mfma_f32_16x16x32_bf16 v[40:43], v[128:131], v[168:171], v[40:43]
	v_mfma_f32_16x16x32_bf16 v[28:31], v[104:107], v[176:179], v[28:31]
	v_mfma_f32_16x16x32_bf16 v[24:27], v[128:131], v[176:179], v[24:27]
	v_mfma_f32_16x16x32_bf16 v[12:15], v[104:107], v[200:203], v[12:15]
	v_mfma_f32_16x16x32_bf16 v[8:11], v[128:131], v[200:203], v[8:11]
	v_mfma_f32_16x16x32_bf16 v[60:63], v[116:119], v[164:167], v[60:63]
	v_mfma_f32_16x16x32_bf16 v[56:59], v[140:143], v[164:167], v[56:59]
	v_mfma_f32_16x16x32_bf16 v[44:47], v[116:119], v[172:175], v[44:47]
	v_mfma_f32_16x16x32_bf16 v[40:43], v[140:143], v[172:175], v[40:43]
	v_mfma_f32_16x16x32_bf16 v[28:31], v[116:119], v[180:183], v[28:31]
	v_mfma_f32_16x16x32_bf16 v[24:27], v[140:143], v[180:183], v[24:27]
	v_mfma_f32_16x16x32_bf16 v[12:15], v[116:119], v[204:207], v[12:15]
	v_mfma_f32_16x16x32_bf16 v[8:11], v[140:143], v[204:207], v[8:11]
	v_mfma_f32_16x16x32_bf16 v[52:55], v[144:147], v[160:163], v[52:55]
	v_mfma_f32_16x16x32_bf16 v[48:51], v[152:155], v[160:163], v[48:51]
	v_mfma_f32_16x16x32_bf16 v[36:39], v[144:147], v[168:171], v[36:39]
	v_mfma_f32_16x16x32_bf16 v[32:35], v[152:155], v[168:171], v[32:35]
	v_mfma_f32_16x16x32_bf16 v[20:23], v[144:147], v[176:179], v[20:23]
	v_mfma_f32_16x16x32_bf16 v[16:19], v[152:155], v[176:179], v[16:19]
	v_mfma_f32_16x16x32_bf16 v[4:7], v[144:147], v[200:203], v[4:7]
	v_mfma_f32_16x16x32_bf16 v[0:3], v[152:155], v[200:203], v[0:3]
	v_mfma_f32_16x16x32_bf16 v[52:55], v[148:151], v[164:167], v[52:55]
	v_mfma_f32_16x16x32_bf16 v[48:51], v[156:159], v[164:167], v[48:51]
	v_mfma_f32_16x16x32_bf16 v[36:39], v[148:151], v[172:175], v[36:39]
	v_mfma_f32_16x16x32_bf16 v[32:35], v[156:159], v[172:175], v[32:35]
	v_mfma_f32_16x16x32_bf16 v[20:23], v[148:151], v[180:183], v[20:23]
	v_mfma_f32_16x16x32_bf16 v[16:19], v[156:159], v[180:183], v[16:19]
	v_mfma_f32_16x16x32_bf16 v[4:7], v[148:151], v[204:207], v[4:7]
	v_mfma_f32_16x16x32_bf16 v[0:3], v[156:159], v[204:207], v[0:3]
	s_barrier
	s_add_i32 s67, s67, 2
	s_add_u32 s65, s65, 0x100
	s_addc_u32 s66, s66, 0
	s_cmp_gt_u32 s67, 61
	s_mov_b64 s[50:51], s[52:53]
	s_cbranch_scc0 .LBB0_1037
	s_and_b64 vcc, exec, s[46:47]
	s_cbranch_vccz .LBB0_1040
	s_barrier
